# baseline (speedup 1.0000x reference)
; #define SBAR() __builtin_amdgcn_sched_barrier(0)
; DEVI void finishSM(f32x16& p0, f32x16& p1, float alpha, float& l_reg, bf16x8& pa0, bf16x8& pa1, bf16x8& pa2, bf16x8& pa3) {
; #pragma unroll
;   for (int r = 0; r < 16; ++r) p1[r] = __builtin_amdgcn_exp2f(p1[r]);
;   float ps = 0;
; #pragma unroll
;   for (int r = 0; r < 16; ++r) ps += p0[r];
; #pragma unroll
;   for (int r = 0; r < 16; ++r) ps += p1[r];
;   { auto rr = __builtin_amdgcn_permlane32_swap(__float_as_uint(ps), __float_as_uint(ps), false, false);
;     ps = __uint_as_float(rr[0]) + __uint_as_float(rr[1]); }
;   l_reg = l_reg * alpha + ps;
;     ...
;   PK4(p0, 0, pa0); PK4(p0, 8, pa1); PK4(p1, 0, pa2); PK4(p1, 8, pa3);
;     ...
; }
; DEVI void mask_tile(f32x16& p0, f32x16& p1, bool nv16) {
; #pragma unroll
;   for (int r = 0; r < 16; ++r) { if (!(nv16 && r < 8)) p0[r] = -1e30f; p1[r] = -1e30f; }
; }
; DEVI void qkt(f32x16& p0, f32x16& p1, const char* Ks, const char* Rs, const bf16x8* qr, const char* Qrs, int r32, int hi) {
;   p0 = f32x16{}; p1 = f32x16{};
; #pragma unroll
;   for (int d0 = 0; d0 < 8; ++d0) { int cb = (d0 * 16 + hi * 8) * 2;
;     bf16x8 b0 = *reinterpret_cast<const bf16x8*>(Ks + KSWZ(r32, cb));
;     bf16x8 b1 = *reinterpret_cast<const bf16x8*>(Ks + KSWZ(32 + r32, cb));
;     p0 = __builtin_amdgcn_mfma_f32_32x32x16_bf16(b0, qr[d0], p0, 0, 0, 0);
;     p1 = __builtin_amdgcn_mfma_f32_32x32x16_bf16(b1, qr[d0], p1, 0, 0, 0); }
; #pragma unroll
;   for (int d0 = 0; d0 < 4; ++d0) { int cb = (d0 * 16 + hi * 8) * 2;
;     bf16x8 b0 = *reinterpret_cast<const bf16x8*>(Rs + RSWZ(r32, cb));
;     bf16x8 b1 = *reinterpret_cast<const bf16x8*>(Rs + RSWZ(32 + r32, cb));
;     bf16x8 qf = *reinterpret_cast<const bf16x8*>(Qrs + RSWZ(r32, cb));
;     p0 = __builtin_amdgcn_mfma_f32_32x32x16_bf16(b0, qf, p0, 0, 0, 0);
;     p1 = __builtin_amdgcn_mfma_f32_32x32x16_bf16(b1, qf, p1, 0, 0, 0); }
; }
; DEVI void attn_item(const u16* __restrict__ Qb, const u16* __restrict__ KNh, const u16* __restrict__ VTh, int Lpad, const u16* __restrict__ KRb,
;                     const u16* __restrict__ SZb, u16* __restrict__ AOb, int NT, char* lds, const int wid_s_) {
;     ...
;   for (int j = 1; j + 1 < NT; j += 2) {
;     SLOAD_KR((j + 1) * 64);
;     SBAR(); qkt(pB0, pB1, K_lds + SHM_K, R_lds + SHM_R, qr, Qrs, r32, hi);
;     finishSM(pA0, pA1, alA, l_reg, pa0, pa1, pa2, pa3); SGB_QK(); SBAR();
.LBB0_981:
	global_load_dwordx4 v[128:131], v168, s[36:37] offset:3072
	v_add_u32_e32 v64, 0x20000, v168
	global_load_dwordx4 v[132:135], v64, s[36:37] offset:3072
	global_load_dwordx4 v[136:139], v166, s[36:37] offset:3072
	ds_read_b128 v[64:67], v187 offset:49152
	v_exp_f32_e32 v242, v80
	s_waitcnt lgkmcnt(0)
	v_mfma_f32_32x32x16_bf16 v[64:79], v[64:67], v[96:99], 0
	ds_read_b128 v[82:85], v187 offset:57344
	v_exp_f32_e32 v245, v81
	s_waitcnt lgkmcnt(0)
	v_mfma_f32_32x32x16_bf16 v[80:95], v[82:85], v[96:99], 0
	ds_read_b128 v[238:241], v188 offset:49152
	v_exp_f32_e32 v248, v152
	s_waitcnt lgkmcnt(0)
	v_mfma_f32_32x32x16_bf16 v[64:79], v[238:241], v[100:103], v[64:79]
	ds_read_b128 v[238:241], v188 offset:57344
	v_exp_f32_e32 v251, v153
	s_waitcnt lgkmcnt(0)
	v_mfma_f32_32x32x16_bf16 v[80:95], v[238:241], v[100:103], v[80:95]
	ds_read_b128 v[238:241], v189 offset:49152
	v_add_f32_e32 v152, v235, v231
	v_add_f32_e32 v152, v230, v152
	v_exp_f32_e32 v252, v150
	s_waitcnt lgkmcnt(0)
	v_mfma_f32_32x32x16_bf16 v[64:79], v[238:241], v[104:107], v[64:79]
	ds_read_b128 v[238:241], v189 offset:57344
	v_add_f32_e32 v150, v232, v152
	v_add_f32_e32 v150, v233, v150
	v_add_f32_e32 v221, v236, v150
	v_exp_f32_e32 v253, v151
	s_waitcnt lgkmcnt(0)
	v_mfma_f32_32x32x16_bf16 v[80:95], v[238:241], v[104:107], v[80:95]
	ds_read_b128 v[150:153], v190 offset:49152
	v_add_f32_e32 v221, v234, v221
	v_add_f32_e32 v221, v237, v221
	v_add_f32_e32 v221, v156, v221
	v_exp_f32_e32 v209, v148
	s_waitcnt lgkmcnt(0)
	v_mfma_f32_32x32x16_bf16 v[64:79], v[150:153], v[108:111], v[64:79]
	ds_read_b128 v[150:153], v190 offset:57344
	v_add_f32_e32 v148, v157, v221
	v_add_f32_e32 v148, v158, v148
	v_add_f32_e32 v221, v159, v148
	v_exp_f32_e32 v210, v149
	s_waitcnt lgkmcnt(0)
	v_mfma_f32_32x32x16_bf16 v[80:95], v[150:153], v[108:111], v[80:95]
	ds_read_b128 v[148:151], v191 offset:49152
	v_add_f32_e32 v152, v228, v221
	v_add_f32_e32 v152, v229, v152
	v_add_f32_e32 v152, v154, v152
	v_exp_f32_e32 v211, v142
	s_waitcnt lgkmcnt(0)
	v_mfma_f32_32x32x16_bf16 v[64:79], v[148:151], v[112:115], v[64:79]
	ds_read_b128 v[148:151], v191 offset:57344
	v_add_f32_e32 v142, v155, v152
	v_add_f32_e32 v142, v242, v142
	v_add_f32_e32 v142, v245, v142
	v_exp_f32_e32 v212, v143
	s_waitcnt lgkmcnt(0)
	v_mfma_f32_32x32x16_bf16 v[80:95], v[148:151], v[112:115], v[80:95]
	ds_read_b128 v[148:151], v192 offset:49152
	v_add_f32_e32 v142, v248, v142
	v_add_f32_e32 v142, v251, v142
	v_add_f32_e32 v142, v252, v142
	v_exp_f32_e32 v214, v146
	s_waitcnt lgkmcnt(0)
	v_mfma_f32_32x32x16_bf16 v[64:79], v[148:151], v[116:119], v[64:79]
	ds_read_b128 v[148:151], v192 offset:57344
	v_add_f32_e32 v142, v253, v142
	v_add_f32_e32 v142, v209, v142
	v_add_f32_e32 v142, v210, v142
	v_exp_f32_e32 v215, v147
	s_waitcnt lgkmcnt(0)
	v_mfma_f32_32x32x16_bf16 v[80:95], v[148:151], v[116:119], v[80:95]
	ds_read_b128 v[146:149], v193 offset:49152
	v_add_f32_e32 v142, v211, v142
	v_add_f32_e32 v142, v212, v142
	v_add_f32_e32 v142, v214, v142
	v_exp_f32_e32 v216, v140
	s_waitcnt lgkmcnt(0)
	v_mfma_f32_32x32x16_bf16 v[64:79], v[146:149], v[120:123], v[64:79]
	ds_read_b128 v[146:149], v193 offset:57344
	v_add_f32_e32 v142, v215, v142
	v_cvt_pk_bf16_f32 v140, v231, v235
	v_add_f32_e32 v142, v216, v142
	v_exp_f32_e32 v217, v141
	s_waitcnt lgkmcnt(0)
	v_mfma_f32_32x32x16_bf16 v[80:95], v[146:149], v[120:123], v[80:95]
	ds_read_b128 v[146:149], v194 offset:49152
	v_add_f32_e32 v143, v217, v142
	v_cvt_pk_bf16_f32 v141, v230, v232
	v_cvt_pk_bf16_f32 v142, v233, v236
	v_exp_f32_e32 v218, v144
	s_waitcnt lgkmcnt(0)
	v_mfma_f32_32x32x16_bf16 v[64:79], v[146:149], v[124:127], v[64:79]
	ds_read_b128 v[146:149], v194 offset:57344
	v_add_f32_e32 v144, v218, v143
	v_cvt_pk_bf16_f32 v143, v234, v237
	v_permlane32_swap_b32_e32 v140, v142
	v_exp_f32_e32 v219, v145
	s_waitcnt lgkmcnt(0)
	v_mfma_f32_32x32x16_bf16 v[80:95], v[146:149], v[124:127], v[80:95]
	ds_read_b128 v[148:151], v195 offset:8192
	v_add_f32_e32 v204, v219, v144
	v_permlane32_swap_b32_e32 v141, v143
	v_mov_b32_e32 v221, v204
	ds_read_b128 v[230:233], v195 offset:12288
	v_cvt_pk_bf16_f32 v144, v156, v157
	v_cvt_pk_bf16_f32 v145, v158, v159
	ds_read_b128 v[156:159], v196
	v_cvt_pk_bf16_f32 v146, v228, v229
	ds_read_b128 v[234:237], v198
	s_waitcnt lgkmcnt(1)
	v_mfma_f32_32x32x16_bf16 v[80:95], v[230:233], v[156:159], v[80:95]
	ds_read_b128 v[228:231], v197 offset:12288
	s_waitcnt lgkmcnt(0)
	v_mfma_f32_32x32x16_bf16 v[80:95], v[228:231], v[234:237], v[80:95]
	ds_read_b128 v[228:231], v199 offset:12288
	ds_read_b128 v[238:241], v200
	s_waitcnt lgkmcnt(0)
	v_mfma_f32_32x32x16_bf16 v[80:95], v[228:231], v[238:241], v[80:95]
	v_permlane32_swap_b32_e32 v204, v221
	v_cvt_pk_bf16_f32 v147, v154, v155
	v_permlane32_swap_b32_e32 v144, v146
	ds_read_b128 v[228:231], v201 offset:12288
	v_mfma_f32_32x32x16_bf16 v[64:79], v[148:151], v[156:159], v[64:79]
	v_permlane32_swap_b32_e32 v145, v147
	ds_read_b128 v[148:151], v197 offset:8192
	v_cvt_pk_bf16_f32 v155, v218, v219
	ds_read_b128 v[156:159], v202
	s_waitcnt lgkmcnt(1)
	v_mfma_f32_32x32x16_bf16 v[64:79], v[148:151], v[234:237], v[64:79]
	ds_read_b128 v[148:151], v199 offset:8192
	v_cvt_pk_bf16_f32 v154, v216, v217
	s_waitcnt lgkmcnt(0)
	v_mfma_f32_32x32x16_bf16 v[64:79], v[148:151], v[238:241], v[64:79]
	ds_read_b128 v[150:153], v201 offset:8192
	s_waitcnt lgkmcnt(0)
; #define SBAR() __builtin_amdgcn_sched_barrier(0)
; #define SGB_QK() _Pragma("unroll") for (int g_ = 0; g_ < 24; ++g_) { __builtin_amdgcn_sched_group_barrier(0x008, 1, 0); __builtin_amdgcn_sched_group_barrier(0x100, 1, 0); \
;     __builtin_amdgcn_sched_group_barrier(0x002, 3, 0); __builtin_amdgcn_sched_group_barrier(0x400, 1, 0); }
; #define SLOAD_V(k0) do { const char* vb_ = (const char*)VTh + (size_t)(k0) * 2; const char* vb2_ = vb_ + vhalf;                \
;     vs0 = *reinterpret_cast<const bf16x8*>(vb_ + vo_v); vs1 = *reinterpret_cast<const bf16x8*>(vb2_ + vo_v); } while (0)
; #define SWRITE_KR(b) do { int kc = sc * 2; *(bf16x8*)(K_lds + (b) * SHM_K + KSWZ(sr, kc)) = ks0; *(bf16x8*)(K_lds + (b) * SHM_K + KSWZ(32 + sr, kc)) = ks1; \
;     *(bf16x8*)(R_lds + (b) * SHM_R + RSWZ(rr_, rc_ * 2)) = rs0; } while (0)
; #define SWRITE_V(b) do { *(bf16x8*)(V_lds + (b) * SHM_V + RSWZ(vd, vc * 16)) = vs0; *(bf16x8*)(V_lds + (b) * SHM_V + RSWZ(vd + 64, vc * 16)) = vs1; } while (0)
; #define SWAIT() asm volatile("s_waitcnt vmcnt(0)" ::: "memory")
; DEVI void partialSM(f32x16& p0, f32x16& p1, float& m_reg, float& mn, float& alpha) {
;   constexpr float C = ASCALE * 1.4426950408889634f;
;   float pmax = p0[0];
; #pragma unroll
;   for (int r = 1; r < 16; ++r) pmax = fmaxf(pmax, p0[r]);
; #pragma unroll
;   for (int r = 0; r < 16; ++r) pmax = fmaxf(pmax, p1[r]);
;   { auto rr = __builtin_amdgcn_permlane32_swap(__float_as_uint(pmax), __float_as_uint(pmax), false, false);
;     pmax = fmaxf(__uint_as_float(rr[0]), __uint_as_float(rr[1])); }
;   if (__builtin_expect(__all(pmax - m_reg <= ATHR / ASCALE), 1)) { mn = m_reg; alpha = 1.f; }
;   else { mn = fmaxf(m_reg, pmax); alpha = __builtin_amdgcn_exp2f((m_reg - mn) * C); m_reg = mn; }
; DEVI void attn_item(const u16* __restrict__ Qb, const u16* __restrict__ KNh, const u16* __restrict__ VTh, int Lpad, const u16* __restrict__ KRb,
;                     const u16* __restrict__ SZb, u16* __restrict__ AOb, int NT, char* lds, const int wid_s_) {
;     ...
;     SBAR(); qkt(pB0, pB1, K_lds + SHM_K, R_lds + SHM_R, qr, Qrs, r32, hi);
;     finishSM(pA0, pA1, alA, l_reg, pa0, pa1, pa2, pa3); SGB_QK(); SBAR();
;     SLOAD_V((j + 1) * 64); SBAR();
;     pv_d0(o, V_lds, r32, hi, pa0, pa1, pa2, pa3); partialSM(pB0, pB1, m_reg, mnB, alB);
;     SWRITE_KR(0);
;     __syncthreads(); SWAIT(); SWRITE_V(0);
;     RESC(alB); __syncthreads();
	v_mfma_f32_32x32x16_bf16 v[64:79], v[150:153], v[156:159], v[64:79]
	v_cvt_pk_bf16_f32 v153, v214, v215
	v_cvt_pk_bf16_f32 v152, v211, v212
	v_cvt_pk_bf16_f32 v151, v209, v210
	v_cvt_pk_bf16_f32 v149, v248, v251
	s_nop 1
	v_permlane32_swap_b32_e32 v149, v151
	v_cvt_pk_bf16_f32 v148, v242, v245
	v_mfma_f32_32x32x16_bf16 v[80:95], v[228:231], v[156:159], v[80:95]
	v_cvt_pk_bf16_f32 v150, v252, v253
	s_nop 1
	v_permlane32_swap_b32_e32 v148, v150
	v_permlane32_swap_b32_e32 v152, v154
	v_permlane32_swap_b32_e32 v153, v155
	global_load_dwordx4 v[228:231], v162, s[36:37] offset:3328
	global_load_dwordx4 v[232:235], v164, s[36:37] offset:3328
	ds_read_b128 v[236:239], v177
	ds_read_b128 v[240:243], v161
	ds_read_b128 v[244:247], v180
	ds_read_b128 v[248:251], v179
	s_waitcnt lgkmcnt(3)
	v_mfma_f32_32x32x16_bf16 v[16:31], v[140:143], v[236:239], v[16:31]
	ds_read_b128 v[236:239], v177 offset:4096
	s_waitcnt lgkmcnt(3)
	v_mfma_f32_32x32x16_bf16 v[16:31], v[144:147], v[240:243], v[16:31]
	ds_read_b128 v[240:243], v161 offset:4096
	s_waitcnt lgkmcnt(1)
	v_mfma_f32_32x32x16_bf16 v[48:63], v[140:143], v[236:239], v[48:63]
	ds_read_b128 v[236:239], v177 offset:8192
	v_mfma_f32_32x32x16_bf16 v[16:31], v[148:151], v[244:247], v[16:31]
	ds_read_b128 v[244:247], v180 offset:4096
	s_waitcnt lgkmcnt(2)
	v_mfma_f32_32x32x16_bf16 v[48:63], v[144:147], v[240:243], v[48:63]
	ds_read_b128 v[240:243], v161 offset:8192
	s_waitcnt lgkmcnt(2)
	v_mfma_f32_32x32x16_bf16 v[32:47], v[140:143], v[236:239], v[32:47]
	ds_read_b128 v[236:239], v177 offset:12288
	v_mfma_f32_32x32x16_bf16 v[16:31], v[152:155], v[248:251], v[16:31]
	ds_read_b128 v[248:251], v179 offset:4096
	s_waitcnt lgkmcnt(3)
	v_mfma_f32_32x32x16_bf16 v[48:63], v[148:151], v[244:247], v[48:63]
	ds_read_b128 v[244:247], v180 offset:8192
	s_waitcnt lgkmcnt(3)
	v_mfma_f32_32x32x16_bf16 v[32:47], v[144:147], v[240:243], v[32:47]
	ds_read_b128 v[240:243], v161 offset:12288
	s_waitcnt lgkmcnt(3)
	v_mfma_f32_32x32x16_bf16 v[0:15], v[140:143], v[236:239], v[0:15]
	v_max_f32_e32 v140, v64, v65
	v_max3_f32 v140, v140, v66, v67
	v_max3_f32 v140, v140, v68, v69
	v_max3_f32 v140, v140, v70, v71
	v_max3_f32 v140, v140, v72, v73
	v_max3_f32 v140, v140, v74, v75
	v_max3_f32 v140, v140, v76, v77
	s_waitcnt lgkmcnt(2)
	v_mfma_f32_32x32x16_bf16 v[48:63], v[152:155], v[248:251], v[48:63]
	ds_read_b128 v[248:251], v179 offset:8192
	v_max3_f32 v140, v140, v78, v79
	v_max3_f32 v140, v140, v80, v81
	v_max3_f32 v140, v140, v82, v83
	v_max3_f32 v140, v140, v84, v85
	v_max3_f32 v140, v140, v86, v87
	v_max3_f32 v140, v140, v88, v89
	s_waitcnt lgkmcnt(2)
	v_mfma_f32_32x32x16_bf16 v[32:47], v[148:151], v[244:247], v[32:47]
	ds_read_b128 v[244:247], v180 offset:12288
	v_max3_f32 v140, v140, v90, v91
	v_max3_f32 v140, v140, v92, v93
	v_max3_f32 v140, v140, v94, v95
	v_mov_b32_e32 v141, v140
	s_nop 1
	v_permlane32_swap_b32_e32 v140, v141
	s_waitcnt lgkmcnt(2)
	v_mfma_f32_32x32x16_bf16 v[0:15], v[144:147], v[240:243], v[0:15]
	v_max_f32_e32 v140, v140, v141
	v_sub_f32_e32 v141, v140, v222
	v_cmp_ge_f32_e32 vcc, s91, v141
	v_max_f32_e32 v140, v222, v140
	s_waitcnt lgkmcnt(1)
	v_mfma_f32_32x32x16_bf16 v[32:47], v[152:155], v[248:251], v[32:47]
	ds_read_b128 v[248:251], v179 offset:12288
	v_sub_f32_e32 v141, v222, v140
	v_mul_f32_e32 v141, 0x3dd53b94, v141
	v_exp_f32_e32 v141, v141
	s_cmp_eq_u64 vcc, exec
	s_cselect_b64 s[8:9], -1, 0
	s_waitcnt vmcnt(2)
	ds_write_b128 v184, v[128:131] offset:32768
	s_waitcnt lgkmcnt(2)
	v_mfma_f32_32x32x16_bf16 v[0:15], v[148:151], v[244:247], v[0:15]
	ds_write_b128 v184, v[132:135] offset:40960
	ds_write_b128 v186, v[136:139]
	s_waitcnt lgkmcnt(0)
	s_barrier
	s_waitcnt vmcnt(0)
	v_cndmask_b32_e64 v224, v141, 1.0, s[8:9]
	v_mfma_f32_32x32x16_bf16 v[0:15], v[152:155], v[248:251], v[0:15]
	v_cmp_gt_f32_e32 vcc, 1.0, v224
	ds_write_b128 v185, v[228:231]
	ds_write_b128 v185, v[232:235] offset:8192
	s_cbranch_vccz .LBB0_985
	s_and_saveexec_b64 s[14:15], s[6:7]
	ds_write_b32 v181, v224 offset:128
	s_or_b64 exec, exec, s[14:15]
	s_waitcnt lgkmcnt(0)
	v_add_u32_e32 v141, v178, v160
	ds_read_b128 v[128:131], v141 offset:224
	ds_read_b128 v[132:135], v141 offset:192
	ds_read_b128 v[136:139], v141 offset:160
	ds_read_b128 v[142:145], v141 offset:128
	s_waitcnt lgkmcnt(3)
	v_pk_mul_f32 v[28:29], v[28:29], v[128:129]
	s_waitcnt lgkmcnt(2)
	v_pk_mul_f32 v[24:25], v[24:25], v[132:133]
	s_waitcnt lgkmcnt(1)
	v_pk_mul_f32 v[20:21], v[20:21], v[136:137]
	v_pk_mul_f32 v[30:31], v[30:31], v[130:131]
	v_pk_mul_f32 v[26:27], v[26:27], v[134:135]
	v_pk_mul_f32 v[22:23], v[22:23], v[138:139]
	s_waitcnt lgkmcnt(0)
	v_pk_mul_f32 v[18:19], v[18:19], v[144:145]
	v_pk_mul_f32 v[16:17], v[16:17], v[142:143]
	v_pk_mul_f32 v[60:61], v[60:61], v[128:129]
	v_pk_mul_f32 v[56:57], v[56:57], v[132:133]
	v_pk_mul_f32 v[52:53], v[52:53], v[136:137]
	v_pk_mul_f32 v[62:63], v[62:63], v[130:131]
	v_pk_mul_f32 v[58:59], v[58:59], v[134:135]
	v_pk_mul_f32 v[54:55], v[54:55], v[138:139]
	v_pk_mul_f32 v[50:51], v[50:51], v[144:145]
	v_pk_mul_f32 v[48:49], v[48:49], v[142:143]
	v_pk_mul_f32 v[44:45], v[44:45], v[128:129]
	v_pk_mul_f32 v[40:41], v[40:41], v[132:133]
	v_pk_mul_f32 v[36:37], v[36:37], v[136:137]
	v_pk_mul_f32 v[46:47], v[46:47], v[130:131]
	v_pk_mul_f32 v[42:43], v[42:43], v[134:135]
	v_pk_mul_f32 v[38:39], v[38:39], v[138:139]
	v_pk_mul_f32 v[34:35], v[34:35], v[144:145]
	v_pk_mul_f32 v[32:33], v[32:33], v[142:143]
	v_pk_mul_f32 v[12:13], v[12:13], v[128:129]
	v_pk_mul_f32 v[8:9], v[8:9], v[132:133]
	v_pk_mul_f32 v[4:5], v[4:5], v[136:137]
	v_pk_mul_f32 v[14:15], v[14:15], v[130:131]
	v_pk_mul_f32 v[10:11], v[10:11], v[134:135]
	v_pk_mul_f32 v[6:7], v[6:7], v[138:139]
	v_pk_mul_f32 v[2:3], v[2:3], v[144:145]
	v_pk_mul_f32 v[0:1], v[0:1], v[142:143]
; #define SBAR() __builtin_amdgcn_sched_barrier(0)
; #define SGB_QK() _Pragma("unroll") for (int g_ = 0; g_ < 24; ++g_) { __builtin_amdgcn_sched_group_barrier(0x008, 1, 0); __builtin_amdgcn_sched_group_barrier(0x100, 1, 0); \
;     __builtin_amdgcn_sched_group_barrier(0x002, 3, 0); __builtin_amdgcn_sched_group_barrier(0x400, 1, 0); }
; #define SLOAD_KR(k0) do { const char* kb_ = (const char*)KNh + (size_t)(k0) * (LDK * 2); const char* kb2_ = kb_ + 32 * LDK * 2; const char* rb_ = (const char*)KRb + (size_t)(k0) * 128; \
;     ks0 = *reinterpret_cast<const bf16x8*>(kb_ + vo_k); ks1 = *reinterpret_cast<const bf16x8*>(kb2_ + vo_k);               \
;     rs0 = *reinterpret_cast<const bf16x8*>(rb_ + vo_r); } while (0)
; DEVI void partialSM(f32x16& p0, f32x16& p1, float& m_reg, float& mn, float& alpha) {
;     ...
;   else { mn = fmaxf(m_reg, pmax); alpha = __builtin_amdgcn_exp2f((m_reg - mn) * C); m_reg = mn; }
;   float mnC = -mn * C;
; #pragma unroll
;   for (int r = 0; r < 16; ++r) p0[r] = fmaf(p0[r], C, mnC);
; #pragma unroll
;   for (int r = 0; r < 16; ++r) p1[r] = fmaf(p1[r], C, mnC);
; #pragma unroll
;   for (int r = 0; r < 16; ++r) p0[r] = __builtin_amdgcn_exp2f(p0[r]);
; }
; DEVI void finishSM(f32x16& p0, f32x16& p1, float alpha, float& l_reg, bf16x8& pa0, bf16x8& pa1, bf16x8& pa2, bf16x8& pa3) {
; #pragma unroll
;   for (int r = 0; r < 16; ++r) p1[r] = __builtin_amdgcn_exp2f(p1[r]);
;   float ps = 0;
; #pragma unroll
;   for (int r = 0; r < 16; ++r) ps += p0[r];
; #pragma unroll
;   for (int r = 0; r < 16; ++r) ps += p1[r];
;   { auto rr = __builtin_amdgcn_permlane32_swap(__float_as_uint(ps), __float_as_uint(ps), false, false);
;     ps = __uint_as_float(rr[0]) + __uint_as_float(rr[1]); }
;   l_reg = l_reg * alpha + ps;
; DEVI void attn_item(const u16* __restrict__ Qb, const u16* __restrict__ KNh, const u16* __restrict__ VTh, int Lpad, const u16* __restrict__ KRb,
;                     const u16* __restrict__ SZb, u16* __restrict__ AOb, int NT, char* lds, const int wid_s_) {
;     ...
;     SLOAD_KR((j + 2) * 64);
;     SBAR(); qkt(pA0, pA1, K_lds, R_lds, qr, Qrs, r32, hi);
;     if (j + 1 == NT - 2) mask_tile(pA0, pA1, true);
;     finishSM(pB0, pB1, alB, l_reg, pa0, pa1, pa2, pa3); SGB_QK(); SBAR();
.LBB0_985:
	v_cndmask_b32_e64 v222, v140, v222, s[8:9]
	v_mul_f32_e32 v152, 0xbdd53b94, v222
	v_fmamk_f32 v66, v66, 0x3dd53b94, v152
	v_fmamk_f32 v67, v67, 0x3dd53b94, v152
	v_exp_f32_e32 v141, v66
	v_add_u32_e32 v66, 0x40000, v168
	v_fmamk_f32 v68, v68, 0x3dd53b94, v152
	v_exp_f32_e32 v236, v67
	v_fmamk_f32 v69, v69, 0x3dd53b94, v152
	v_exp_f32_e32 v237, v68
	v_add_u32_e32 v68, 0x60000, v168
	v_fmamk_f32 v128, v64, 0x3dd53b94, v152
	v_exp_f32_e32 v238, v69
	v_exp_f32_e32 v140, v128
	s_waitcnt lgkmcnt(0)
	s_barrier
	global_load_dwordx4 v[128:131], v66, s[36:37] offset:3072
	v_add_u32_e32 v66, 0x2000, v166
	global_load_dwordx4 v[132:135], v68, s[36:37] offset:3072
	global_load_dwordx4 v[136:139], v66, s[36:37] offset:3072
	v_fmamk_f32 v74, v74, 0x3dd53b94, v152
	v_fmamk_f32 v75, v75, 0x3dd53b94, v152
	v_exp_f32_e32 v228, v74
	v_exp_f32_e32 v229, v75
	v_fmamk_f32 v65, v65, 0x3dd53b94, v152
	v_fmamk_f32 v70, v70, 0x3dd53b94, v152
	v_fmamk_f32 v71, v71, 0x3dd53b94, v152
	v_fmamk_f32 v72, v72, 0x3dd53b94, v152
	v_fmamk_f32 v73, v73, 0x3dd53b94, v152
	v_fmamk_f32 v76, v76, 0x3dd53b94, v152
	v_fmamk_f32 v77, v77, 0x3dd53b94, v152
	v_fmamk_f32 v78, v78, 0x3dd53b94, v152
	v_fmamk_f32 v79, v79, 0x3dd53b94, v152
	v_fmamk_f32 v64, v80, 0x3dd53b94, v152
	v_fmamk_f32 v80, v81, 0x3dd53b94, v152
	v_fmamk_f32 v241, v82, 0x3dd53b94, v152
	v_fmamk_f32 v145, v83, 0x3dd53b94, v152
	v_fmamk_f32 v144, v84, 0x3dd53b94, v152
	v_fmamk_f32 v143, v85, 0x3dd53b94, v152
	v_fmamk_f32 v142, v86, 0x3dd53b94, v152
	v_fmamk_f32 v239, v87, 0x3dd53b94, v152
	v_fmamk_f32 v154, v88, 0x3dd53b94, v152
	v_fmamk_f32 v150, v89, 0x3dd53b94, v152
	v_fmamk_f32 v146, v90, 0x3dd53b94, v152
	v_fmamk_f32 v147, v91, 0x3dd53b94, v152
	v_fmamk_f32 v148, v92, 0x3dd53b94, v152
	v_exp_f32_e32 v240, v65
	v_exp_f32_e32 v234, v70
	v_exp_f32_e32 v235, v71
	v_exp_f32_e32 v232, v72
	v_exp_f32_e32 v233, v73
	v_exp_f32_e32 v230, v76
	v_exp_f32_e32 v231, v77
	v_exp_f32_e32 v153, v78
	v_exp_f32_e32 v155, v79
	v_fmamk_f32 v149, v93, 0x3dd53b94, v152
	v_fmamk_f32 v151, v94, 0x3dd53b94, v152
	v_fmac_f32_e32 v152, 0x3dd53b94, v95
	ds_read_b128 v[66:69], v187 offset:32768
	v_add_f32_e32 v65, v240, v140
	v_add_f32_e32 v81, v141, v65
	v_exp_f32_e32 v209, v64
	s_cmp_eq_u32 s4, s2
	s_cselect_b64 vcc, -1, 0
	s_waitcnt lgkmcnt(0)
	v_mfma_f32_32x32x16_bf16 v[64:79], v[66:69], v[96:99], 0
	ds_read_b128 v[82:85], v187 offset:40960
	v_add_f32_e32 v81, v236, v81
	v_add_f32_e32 v81, v237, v81
	v_add_f32_e32 v210, v238, v81
	v_exp_f32_e32 v211, v80
	s_waitcnt lgkmcnt(0)
	v_mfma_f32_32x32x16_bf16 v[80:95], v[82:85], v[96:99], 0
	ds_read_b128 v[170:173], v188 offset:32768
	v_add_f32_e32 v210, v234, v210
	v_add_f32_e32 v210, v235, v210
	v_add_f32_e32 v210, v232, v210
	v_exp_f32_e32 v212, v241
	s_waitcnt lgkmcnt(0)
	v_mfma_f32_32x32x16_bf16 v[64:79], v[170:173], v[100:103], v[64:79]
	ds_read_b128 v[170:173], v188 offset:40960
	v_add_f32_e32 v210, v233, v210
	v_add_f32_e32 v210, v228, v210
	v_add_f32_e32 v210, v229, v210
	v_exp_f32_e32 v214, v145
	s_waitcnt lgkmcnt(0)
	v_mfma_f32_32x32x16_bf16 v[80:95], v[170:173], v[100:103], v[80:95]
	ds_read_b128 v[170:173], v189 offset:32768
	v_add_f32_e32 v145, v230, v210
	v_add_f32_e32 v145, v231, v145
	v_add_f32_e32 v145, v153, v145
	v_exp_f32_e32 v210, v144
	s_waitcnt lgkmcnt(0)
	v_mfma_f32_32x32x16_bf16 v[64:79], v[170:173], v[104:107], v[64:79]
	ds_read_b128 v[170:173], v189 offset:40960
	v_add_f32_e32 v144, v155, v145
	v_add_f32_e32 v144, v209, v144
	v_add_f32_e32 v144, v211, v144
	v_exp_f32_e32 v215, v143
	s_waitcnt lgkmcnt(0)
	v_mfma_f32_32x32x16_bf16 v[80:95], v[170:173], v[104:107], v[80:95]
	ds_read_b128 v[170:173], v190 offset:32768
	v_add_f32_e32 v143, v212, v144
	v_add_f32_e32 v143, v214, v143
	v_add_f32_e32 v216, v210, v143
	v_exp_f32_e32 v217, v142
	s_waitcnt lgkmcnt(0)
	v_mfma_f32_32x32x16_bf16 v[64:79], v[170:173], v[108:111], v[64:79]
	ds_read_b128 v[142:145], v190 offset:40960
	v_add_f32_e32 v170, v215, v216
	v_cvt_pk_bf16_f32 v140, v140, v240
	v_add_f32_e32 v216, v217, v170
	v_exp_f32_e32 v218, v239
	s_waitcnt lgkmcnt(0)
	v_mfma_f32_32x32x16_bf16 v[80:95], v[142:145], v[108:111], v[80:95]
	ds_read_b128 v[170:173], v191 offset:32768
	v_cvt_pk_bf16_f32 v141, v141, v236
	v_cvt_pk_bf16_f32 v142, v237, v238
	v_add_f32_e32 v143, v218, v216
	v_exp_f32_e32 v154, v154
	s_waitcnt lgkmcnt(0)
	v_mfma_f32_32x32x16_bf16 v[64:79], v[170:173], v[112:115], v[64:79]
	ds_read_b128 v[170:173], v191 offset:40960
	v_add_f32_e32 v144, v154, v143
	v_cvt_pk_bf16_f32 v143, v234, v235
	v_permlane32_swap_b32_e32 v140, v142
	v_exp_f32_e32 v216, v150
	s_waitcnt lgkmcnt(0)
	v_mfma_f32_32x32x16_bf16 v[80:95], v[170:173], v[112:115], v[80:95]
	ds_read_b128 v[170:173], v192 offset:32768
	v_add_f32_e32 v145, v216, v144
	v_permlane32_swap_b32_e32 v141, v143
	v_cvt_pk_bf16_f32 v144, v232, v233
	v_exp_f32_e32 v219, v146
	s_waitcnt lgkmcnt(0)
	v_mfma_f32_32x32x16_bf16 v[64:79], v[170:173], v[116:119], v[64:79]
	ds_read_b128 v[170:173], v192 offset:40960
	v_add_f32_e32 v150, v219, v145
	v_cvt_pk_bf16_f32 v145, v228, v229
	v_cvt_pk_bf16_f32 v146, v230, v231
	v_exp_f32_e32 v236, v147
	s_waitcnt lgkmcnt(0)
	v_mfma_f32_32x32x16_bf16 v[80:95], v[170:173], v[116:119], v[80:95]
	ds_read_b128 v[170:173], v193 offset:32768
	v_add_f32_e32 v150, v236, v150
	v_cvt_pk_bf16_f32 v147, v153, v155
	v_permlane32_swap_b32_e32 v144, v146
	v_exp_f32_e32 v155, v148
	s_waitcnt lgkmcnt(0)
	v_mfma_f32_32x32x16_bf16 v[64:79], v[170:173], v[120:123], v[64:79]
	ds_read_b128 v[170:173], v193 offset:40960
	v_add_f32_e32 v150, v155, v150
	v_permlane32_swap_b32_e32 v145, v147
	v_cvt_pk_bf16_f32 v148, v209, v211
	v_exp_f32_e32 v209, v149
	s_waitcnt lgkmcnt(0)
; DEVI void mask_tile(f32x16& p0, f32x16& p1, bool nv16) {
; #pragma unroll
;   for (int r = 0; r < 16; ++r) { if (!(nv16 && r < 8)) p0[r] = -1e30f; p1[r] = -1e30f; }
; }
; DEVI void qkt(f32x16& p0, f32x16& p1, const char* Ks, const char* Rs, const bf16x8* qr, const char* Qrs, int r32, int hi) {
;   p0 = f32x16{}; p1 = f32x16{};
; #pragma unroll
;   for (int d0 = 0; d0 < 8; ++d0) { int cb = (d0 * 16 + hi * 8) * 2;
;     bf16x8 b0 = *reinterpret_cast<const bf16x8*>(Ks + KSWZ(r32, cb));
;     bf16x8 b1 = *reinterpret_cast<const bf16x8*>(Ks + KSWZ(32 + r32, cb));
;     p0 = __builtin_amdgcn_mfma_f32_32x32x16_bf16(b0, qr[d0], p0, 0, 0, 0);
;     p1 = __builtin_amdgcn_mfma_f32_32x32x16_bf16(b1, qr[d0], p1, 0, 0, 0); }
; #pragma unroll
;   for (int d0 = 0; d0 < 4; ++d0) { int cb = (d0 * 16 + hi * 8) * 2;
;     bf16x8 b0 = *reinterpret_cast<const bf16x8*>(Rs + RSWZ(r32, cb));
;     bf16x8 b1 = *reinterpret_cast<const bf16x8*>(Rs + RSWZ(32 + r32, cb));
;     bf16x8 qf = *reinterpret_cast<const bf16x8*>(Qrs + RSWZ(r32, cb));
;     p0 = __builtin_amdgcn_mfma_f32_32x32x16_bf16(b0, qf, p0, 0, 0, 0);
;     p1 = __builtin_amdgcn_mfma_f32_32x32x16_bf16(b1, qf, p1, 0, 0, 0); }
; }
; DEVI void pv_d0(f32x16* o, const char* Vs, int r32, int hi, bf16x8 pa0, bf16x8 pa1, bf16x8 pa2, bf16x8 pa3) {
; #pragma unroll
;   for (int d0 = 0; d0 < 4; ++d0) {
;     const bf16x8 f0 = *reinterpret_cast<const bf16x8*>(Vs + RSWZ(d0 * 32 + r32, (0 * 16 + hi * 8) * 2));
;     const bf16x8 f1 = *reinterpret_cast<const bf16x8*>(Vs + RSWZ(d0 * 32 + r32, (1 * 16 + hi * 8) * 2));
;     const bf16x8 f2 = *reinterpret_cast<const bf16x8*>(Vs + RSWZ(d0 * 32 + r32, (2 * 16 + hi * 8) * 2));
;     const bf16x8 f3 = *reinterpret_cast<const bf16x8*>(Vs + RSWZ(d0 * 32 + r32, (3 * 16 + hi * 8) * 2));
;     o[d0] = __builtin_amdgcn_mfma_f32_32x32x16_bf16(pa0, f0, o[d0], 0, 0, 0);
;     o[d0] = __builtin_amdgcn_mfma_f32_32x32x16_bf16(pa1, f1, o[d0], 0, 0, 0);
;     o[d0] = __builtin_amdgcn_mfma_f32_32x32x16_bf16(pa2, f2, o[d0], 0, 0, 0);
;     o[d0] = __builtin_amdgcn_mfma_f32_32x32x16_bf16(pa3, f3, o[d0], 0, 0, 0);
;   }
; }
	v_mfma_f32_32x32x16_bf16 v[80:95], v[170:173], v[120:123], v[80:95]
	ds_read_b128 v[170:173], v194 offset:32768
	v_add_f32_e32 v153, v209, v150
	v_cvt_pk_bf16_f32 v149, v212, v214
	v_cvt_pk_bf16_f32 v150, v210, v215
	v_exp_f32_e32 v210, v151
	s_waitcnt lgkmcnt(0)
	v_mfma_f32_32x32x16_bf16 v[64:79], v[170:173], v[124:127], v[64:79]
	ds_read_b128 v[170:173], v194 offset:40960
	v_add_f32_e32 v153, v210, v153
	v_cvt_pk_bf16_f32 v151, v217, v218
	v_permlane32_swap_b32_e32 v148, v150
	v_exp_f32_e32 v211, v152
	s_waitcnt lgkmcnt(0)
	v_mfma_f32_32x32x16_bf16 v[80:95], v[170:173], v[124:127], v[80:95]
	ds_read_b128 v[228:231], v195
	v_add_f32_e32 v170, v211, v153
	v_mov_b32_e32 v171, v170
	v_permlane32_swap_b32_e32 v149, v151
	ds_read_b128 v[232:235], v195 offset:4096
	v_permlane32_swap_b32_e32 v170, v171
	v_cvt_pk_bf16_f32 v152, v154, v216
	v_cvt_pk_bf16_f32 v153, v219, v236
	ds_read_b128 v[236:239], v196
	s_waitcnt lgkmcnt(0)
	v_mfma_f32_32x32x16_bf16 v[64:79], v[228:231], v[236:239], v[64:79]
	ds_read_b128 v[228:231], v197
	v_mfma_f32_32x32x16_bf16 v[80:95], v[232:235], v[236:239], v[80:95]
	ds_read_b128 v[240:243], v198
	ds_read_b128 v[232:235], v202
	ds_read_b128 v[236:239], v199 offset:4096
	s_waitcnt lgkmcnt(2)
	v_mfma_f32_32x32x16_bf16 v[64:79], v[228:231], v[240:243], v[64:79]
	ds_read_b128 v[228:231], v199
	ds_read_b128 v[244:247], v200
	s_waitcnt lgkmcnt(0)
	v_mfma_f32_32x32x16_bf16 v[64:79], v[228:231], v[244:247], v[64:79]
	ds_read_b128 v[228:231], v201
	s_waitcnt lgkmcnt(0)
	v_mfma_f32_32x32x16_bf16 v[64:79], v[228:231], v[232:235], v[64:79]
	ds_read_b128 v[226:229], v197 offset:4096
	s_waitcnt lgkmcnt(0)
	v_mfma_f32_32x32x16_bf16 v[80:95], v[226:229], v[240:243], v[80:95]
	ds_read_b128 v[240:243], v201 offset:4096
	v_cvt_pk_bf16_f32 v154, v155, v209
	v_cvt_pk_bf16_f32 v155, v210, v211
	s_nop 0
	v_permlane32_swap_b32_e32 v152, v154
	v_permlane32_swap_b32_e32 v153, v155
	v_mfma_f32_32x32x16_bf16 v[80:95], v[236:239], v[244:247], v[80:95]
	s_nop 1
	v_cndmask_b32_e32 v229, v72, v208, vcc
	v_cndmask_b32_e32 v227, v76, v208, vcc
	v_cndmask_b32_e32 v228, v73, v208, vcc
	s_waitcnt lgkmcnt(0)
	v_mfma_f32_32x32x16_bf16 v[80:95], v[240:243], v[232:235], v[80:95]
	s_nop 11
	v_cndmask_b32_e32 v73, v95, v208, vcc
	v_cndmask_b32_e32 v226, v74, v208, vcc
	v_cndmask_b32_e32 v172, v79, v208, vcc
	v_cndmask_b32_e32 v173, v78, v208, vcc
	v_cndmask_b32_e32 v223, v77, v208, vcc
	v_cndmask_b32_e32 v225, v75, v208, vcc
	v_cndmask_b32_e32 v72, v94, v208, vcc
	v_cndmask_b32_e32 v75, v93, v208, vcc
	v_cndmask_b32_e32 v74, v92, v208, vcc
	v_cndmask_b32_e32 v77, v91, v208, vcc
	v_cndmask_b32_e32 v76, v90, v208, vcc
	v_cndmask_b32_e32 v79, v89, v208, vcc
	v_cndmask_b32_e32 v78, v88, v208, vcc
	v_cndmask_b32_e32 v87, v87, v208, vcc
	v_cndmask_b32_e32 v86, v86, v208, vcc
	v_cndmask_b32_e32 v85, v85, v208, vcc
	v_cndmask_b32_e32 v84, v84, v208, vcc
	v_cndmask_b32_e32 v83, v83, v208, vcc
	v_cndmask_b32_e32 v82, v82, v208, vcc
	v_cndmask_b32_e32 v81, v81, v208, vcc
	v_cndmask_b32_e32 v80, v80, v208, vcc
	global_load_dwordx4 v[90:93], v162, s[36:37] offset:3456
	global_load_dwordx4 v[156:159], v164, s[36:37] offset:3456
	ds_read_b128 v[230:233], v177 offset:16384
	ds_read_b128 v[234:237], v161 offset:16384
	ds_read_b128 v[238:241], v180 offset:16384
	s_waitcnt lgkmcnt(2)
	v_mfma_f32_32x32x16_bf16 v[16:31], v[140:143], v[230:233], v[16:31]
	ds_read_b128 v[230:233], v177 offset:20480
	v_max_f32_e32 v88, v64, v65
	v_max3_f32 v88, v88, v66, v67
	v_max3_f32 v88, v88, v68, v69
	ds_read_b128 v[242:245], v179 offset:16384
	v_max3_f32 v88, v88, v70, v71
	v_max3_f32 v88, v88, v229, v228
	s_waitcnt lgkmcnt(1)
	v_mfma_f32_32x32x16_bf16 v[48:63], v[140:143], v[230:233], v[48:63]
	ds_read_b128 v[230:233], v177 offset:24576
	v_max3_f32 v88, v88, v226, v225
	v_max3_f32 v88, v88, v227, v223
	v_max3_f32 v88, v88, v173, v172
	v_max3_f32 v88, v88, v80, v81
	v_max3_f32 v88, v88, v82, v83
	v_max3_f32 v88, v88, v84, v85
	v_mfma_f32_32x32x16_bf16 v[16:31], v[144:147], v[234:237], v[16:31]
	ds_read_b128 v[234:237], v161 offset:20480
	v_max3_f32 v88, v88, v86, v87
	v_max3_f32 v88, v88, v78, v79
	v_max3_f32 v88, v88, v76, v77
	v_max3_f32 v88, v88, v74, v75
	v_max3_f32 v88, v88, v72, v73
	v_mov_b32_e32 v89, v88
	s_waitcnt lgkmcnt(1)
	v_mfma_f32_32x32x16_bf16 v[32:47], v[140:143], v[230:233], v[32:47]
	ds_read_b128 v[230:233], v177 offset:28672
	v_permlane32_swap_b32_e32 v88, v89
	v_max_f32_e32 v88, v88, v89
	v_sub_f32_e32 v89, v88, v222
	s_waitcnt lgkmcnt(1)
	v_mfma_f32_32x32x16_bf16 v[48:63], v[144:147], v[234:237], v[48:63]
	ds_read_b128 v[234:237], v161 offset:24576
	v_cmp_ge_f32_e32 vcc, s91, v89
	v_max_f32_e32 v89, v222, v88
	v_sub_f32_e32 v88, v222, v89
	v_mul_f32_e32 v88, 0x3dd53b94, v88
	v_exp_f32_e32 v88, v88
	s_waitcnt lgkmcnt(1)
	v_mfma_f32_32x32x16_bf16 v[0:15], v[140:143], v[230:233], v[0:15]
	s_cmp_eq_u64 vcc, exec
	s_cselect_b64 s[8:9], -1, 0
	v_cndmask_b32_e64 v88, v88, 1.0, s[8:9]
	v_cmp_gt_f32_e32 vcc, 1.0, v88
	v_mfma_f32_32x32x16_bf16 v[16:31], v[148:151], v[238:241], v[16:31]
	ds_read_b128 v[238:241], v180 offset:20480
	s_waitcnt lgkmcnt(1)
	v_mfma_f32_32x32x16_bf16 v[32:47], v[144:147], v[234:237], v[32:47]
	ds_read_b128 v[234:237], v161 offset:28672
	s_waitcnt lgkmcnt(1)
	v_mfma_f32_32x32x16_bf16 v[48:63], v[148:151], v[238:241], v[48:63]
	ds_read_b128 v[238:241], v180 offset:24576
	s_waitcnt lgkmcnt(1)
	v_mfma_f32_32x32x16_bf16 v[0:15], v[144:147], v[234:237], v[0:15]
	v_mfma_f32_32x32x16_bf16 v[16:31], v[152:155], v[242:245], v[16:31]
	ds_read_b128 v[242:245], v179 offset:20480
	s_waitcnt lgkmcnt(1)
	v_mfma_f32_32x32x16_bf16 v[32:47], v[148:151], v[238:241], v[32:47]
	ds_read_b128 v[238:241], v180 offset:28672
	s_waitcnt lgkmcnt(1)
	v_mfma_f32_32x32x16_bf16 v[48:63], v[152:155], v[242:245], v[48:63]
	ds_read_b128 v[242:245], v179 offset:24576
	s_waitcnt lgkmcnt(1)
	v_mfma_f32_32x32x16_bf16 v[0:15], v[148:151], v[238:241], v[0:15]
	s_waitcnt lgkmcnt(0)
	v_mfma_f32_32x32x16_bf16 v[32:47], v[152:155], v[242:245], v[32:47]
	ds_read_b128 v[242:245], v179 offset:28672
	s_waitcnt vmcnt(2)
	ds_write_b128 v184, v[128:131] offset:49152
	ds_write_b128 v184, v[132:135] offset:57344
	ds_write_b128 v203, v[136:139]
	s_waitcnt lgkmcnt(0)
	s_barrier
; #define SWRITE_KR(b) do { int kc = sc * 2; *(bf16x8*)(K_lds + (b) * SHM_K + KSWZ(sr, kc)) = ks0; *(bf16x8*)(K_lds + (b) * SHM_K + KSWZ(32 + sr, kc)) = ks1; \
;     *(bf16x8*)(R_lds + (b) * SHM_R + RSWZ(rr_, rc_ * 2)) = rs0; } while (0)
; #define SWRITE_V(b) do { *(bf16x8*)(V_lds + (b) * SHM_V + RSWZ(vd, vc * 16)) = vs0; *(bf16x8*)(V_lds + (b) * SHM_V + RSWZ(vd + 64, vc * 16)) = vs1; } while (0)
; #define SWAIT() asm volatile("s_waitcnt vmcnt(0)" ::: "memory")
; #define RESC(a) do { if (__any((a) < 1.f)) { if (hi == 0) al_l[r32] = (a); asm volatile("s_waitcnt lgkmcnt(0)" ::: "memory"); \
;     _Pragma("unroll") for (int d = 0; d < 4; ++d) _Pragma("unroll") for (int r = 0; r < 16; ++r) o[d][r] *= al_l[crow(r, hi)]; } } while (0)
; DEVI void attn_item(const u16* __restrict__ Qb, const u16* __restrict__ KNh, const u16* __restrict__ VTh, int Lpad, const u16* __restrict__ KRb,
;                     const u16* __restrict__ SZb, u16* __restrict__ AOb, int NT, char* lds, const int wid_s_) {
;     ...
;     SWRITE_KR(1);
;     __syncthreads(); SWAIT(); SWRITE_V(1);
;     RESC(alA); __syncthreads();
	v_mfma_f32_32x32x16_bf16 v[0:15], v[152:155], v[242:245], v[0:15]
	s_waitcnt vmcnt(0)
	ds_write_b128 v185, v[90:93] offset:16384
	ds_write_b128 v185, v[156:159] offset:24576
	s_cbranch_vccz .LBB0_989
	s_and_saveexec_b64 s[14:15], s[6:7]
	ds_write_b32 v181, v88 offset:128
	s_or_b64 exec, exec, s[14:15]
	s_waitcnt lgkmcnt(0)
	v_add_u32_e32 v94, v178, v160
	ds_read_b128 v[90:93], v94 offset:224
	ds_read_b128 v[128:131], v94 offset:192
	ds_read_b128 v[132:135], v94 offset:160
	ds_read_b128 v[136:139], v94 offset:128
	s_waitcnt lgkmcnt(3)
	v_pk_mul_f32 v[28:29], v[28:29], v[90:91]
	s_waitcnt lgkmcnt(2)
	v_pk_mul_f32 v[24:25], v[24:25], v[128:129]
	s_waitcnt lgkmcnt(1)
	v_pk_mul_f32 v[20:21], v[20:21], v[132:133]
	v_pk_mul_f32 v[30:31], v[30:31], v[92:93]
	v_pk_mul_f32 v[26:27], v[26:27], v[130:131]
	v_pk_mul_f32 v[22:23], v[22:23], v[134:135]
	s_waitcnt lgkmcnt(0)
	v_pk_mul_f32 v[18:19], v[18:19], v[138:139]
	v_pk_mul_f32 v[16:17], v[16:17], v[136:137]
	v_pk_mul_f32 v[60:61], v[60:61], v[90:91]
	v_pk_mul_f32 v[56:57], v[56:57], v[128:129]
	v_pk_mul_f32 v[52:53], v[52:53], v[132:133]
	v_pk_mul_f32 v[62:63], v[62:63], v[92:93]
	v_pk_mul_f32 v[58:59], v[58:59], v[130:131]
	v_pk_mul_f32 v[54:55], v[54:55], v[134:135]
	v_pk_mul_f32 v[50:51], v[50:51], v[138:139]
	v_pk_mul_f32 v[48:49], v[48:49], v[136:137]
	v_pk_mul_f32 v[44:45], v[44:45], v[90:91]
	v_pk_mul_f32 v[40:41], v[40:41], v[128:129]
	v_pk_mul_f32 v[36:37], v[36:37], v[132:133]
	v_pk_mul_f32 v[46:47], v[46:47], v[92:93]
	v_pk_mul_f32 v[42:43], v[42:43], v[130:131]
	v_pk_mul_f32 v[38:39], v[38:39], v[134:135]
	v_pk_mul_f32 v[34:35], v[34:35], v[138:139]
	v_pk_mul_f32 v[32:33], v[32:33], v[136:137]
	v_pk_mul_f32 v[12:13], v[12:13], v[90:91]
	v_pk_mul_f32 v[8:9], v[8:9], v[128:129]
	v_pk_mul_f32 v[4:5], v[4:5], v[132:133]
	v_pk_mul_f32 v[14:15], v[14:15], v[92:93]
	v_pk_mul_f32 v[10:11], v[10:11], v[130:131]
	v_pk_mul_f32 v[6:7], v[6:7], v[134:135]
	v_pk_mul_f32 v[2:3], v[2:3], v[138:139]
	v_pk_mul_f32 v[0:1], v[0:1], v[136:137]
